# speedup vs baseline: 1.0012x; 1.0012x over previous
;     __device__ __forceinline__ bf16_t* Ksf() const { return (bf16_t*)(ws + OFF_Ksf); }
;     __device__ __forceinline__ bf16_t* VsfT() const { return (bf16_t*)(ws + OFF_VsfT); }
;     __device__ __forceinline__ bf16_t* Ksb() const { return (bf16_t*)(ws + OFF_Ksb); }
;     __device__ __forceinline__ bf16_t* VsbT() const { return (bf16_t*)(ws + OFF_VsbT); }
; DEV int tid_opaque() { int t = threadIdx.x; asm volatile("" : "+v"(t)); return t; }
; DEV void st_bf4(bf16_t* p, float a, float b, float c, float d) { uint2 w; w.x = pk_bf16(a, b); w.y = pk_bf16(c, d); *(uint2*)p = w; }
; DEV void cache_convert(const Params& p, int l, int vb, int vnb, float* sm) {
;     const int gt = vb * 256 + tid_opaque(), gn = vnb * 256;
;     for (int i = gt; i < 8 * PAST * 96; i += gn) {
;         const int b = i / (PAST * 96), rem = i % (PAST * 96);
;         const float4 v = *(const float4*)(p.cache_fox_k + ((size_t)(l * 8 + b) * PAST * 384) + (size_t)rem * 4);
;         st_bf4(p.Ksf() + (size_t)b * KSP * 384 + (size_t)rem * 4, v.x, v.y, v.z, v.w);
;     }
;     for (int i = gt; i < 8 * PAST * 64; i += gn) {
;         const int b = i / (PAST * 64), rem = i % (PAST * 64);
;         const float4 v = *(const float4*)(p.cache_sb_k + ((size_t)(l * 8 + b) * PAST * 256) + (size_t)rem * 4);
;         st_bf4(p.Ksb() + (size_t)b * KSP * 256 + (size_t)rem * 4, v.x, v.y, v.z, v.w);
;     }
;     for (int i = gt; i < 8 * 48 * 384; i += gn) { const int b = i / (48 * 384), rem = i % (48 * 384); p.Ksf()[(size_t)b * KSP * 384 + (size_t)2064 * 384 + rem] = 0; }
;     for (int i = gt; i < 8 * 48 * 256; i += gn) { const int b = i / (48 * 256), rem = i % (48 * 256); p.Ksb()[(size_t)b * KSP * 256 + (size_t)2064 * 256 + rem] = 0; }
;     for (int i = gt; i < 8 * 384 * 48; i += gn) { const int row = i / 48, c = i % 48; p.VsfT()[(size_t)row * KSP + 2064 + c] = 0; }
;     for (int i = gt; i < 8 * 256 * 48; i += gn) { const int row = i / 48, c = i % 48; p.VsbT()[(size_t)row * KSP + 2064 + c] = 0; }
.Lcc_skip:
	v_lshl_add_u32 v0, s6, 8, v0
	s_cmp_eq_u32 s82, 4
	s_cbranch_scc0 .Lcc_e
	v_mov_b32_e32 v0, 0x1000000

;     __device__ __forceinline__ bf16_t* VsfT() const { return (bf16_t*)(ws + OFF_VsfT); }
;     __device__ __forceinline__ bf16_t* VsbT() const { return (bf16_t*)(ws + OFF_VsbT); }
; DEV void cache_convert(const Params& p, int l, int vb, int vnb, float* sm) {
;     ...
;     for (int job = vb; job < 8 * 192 + 8 * 128; job += vnb) {
;         const bool fox = job < 8 * 192;
;         const int jj = fox ? job : job - 8 * 192, per = fox ? 192 : 128, W = fox ? 384 : 256;
;         const int b = jj / per, r = jj % per, tn = r / 32, tk = r % 32;
;         const float* src = (fox ? p.cache_fox_v : p.cache_sb_v) + (size_t)(l * 8 + b) * PAST * W + (size_t)tk * 64 * W;
;         bf16_t* dst = (fox ? p.VsfT() : p.VsbT()) + ((size_t)b * W + tn * 64) * KSP + tk * 64;
;         transpose_tile(src, W, tn * 64, tn * 64 + 32, dst, KSP, sm);
;     }
.LBB0_2747:
	s_or_b64 exec, exec, s[0:1]
	s_cmp_eq_u32 s82, 8
	s_cbranch_scc1 .LBB0_2750
	s_cmpk_gt_i32 s6, 0x9ff
	s_cbranch_scc1 .LBB0_2750
	s_and_b64 s[0:1], s[94:95], exec
	s_cselect_b32 s0, 0, 8
	s_movk_i32 s14, 0x180
	s_movk_i32 s15, 0x1080
	s_movk_i32 s16, 0x104
